# attention item epilogue: all 16 sub-LN gain loads issued up front, the 15 per-group vmcnt(0) waits that drained each store removed
# speedup vs baseline: 1.0081x; 1.0081x over previous
; __device__ __forceinline__ unsigned pk2(float lo, float hi) { f32x2 v = {lo, hi}; bf16x2_t b = __builtin_convertvector(v, bf16x2_t); return __builtin_bit_cast(unsigned, b); }
; __device__ __forceinline__ float half_swap_sum(float v) { auto rr = __builtin_amdgcn_permlane32_swap(__float_as_uint(v), __float_as_uint(v), false, false); return __uint_as_float(rr[0]) + __uint_as_float(rr[1]); }
; __device__ __forceinline__ void attn_item(LAS unsigned char* lds, const bf16_t* Q, const bf16_t* Kb, const bf16_t* VT, bf16_t* aout, const float* subg, float lam, float omli, float kbound, int head, int qb) {
;     ...
;     if (comp == 0) {
;         float ss = 0.f;
; #pragma unroll
;         for (int e = 0; e < 4; ++e)
; #pragma unroll
;             for (int i = 0; i < 16; ++i) { const float o = O[e][i] * inv - lam * X[(qt * 128 + 32 * e + (i & 3) + 8 * (i >> 2) + 4 * hh) * 32 + r]; O[e][i] = o; ss += o * o; }
;         ss = half_swap_sum(ss);
;         const float rn = __builtin_amdgcn_rsqf(ss * (1.f / 128.f) + EPS) * omli;
;         bf16_t* ap = aout + (size_t)q * 1024 + head * 128 + 4 * hh;
; #pragma unroll
;         for (int e = 0; e < 4; ++e)
; #pragma unroll
;             for (int g4 = 0; g4 < 4; ++g4) { const int e0 = 32 * e + 8 * g4; const f32x4 sg = *(const f32x4*)(subg + e0 + 4 * hh);
;                 u32x2 w; w.x = pk2(O[e][4 * g4 + 0] * rn * sg[0], O[e][4 * g4 + 1] * rn * sg[1]); w.y = pk2(O[e][4 * g4 + 2] * rn * sg[2], O[e][4 * g4 + 3] * rn * sg[3]);
;                 *(u32x2*)(ap + e0) = w; }
.LBB0_328:
	s_andn2_b64 vcc, exec, s[4:5]
	s_waitcnt lgkmcnt(0)
	s_barrier
	s_cbranch_vccnz .LBB0_330
	s_lshl_b32 s0, s0, 14
	v_add3_u32 v64, v65, v64, s0
	ds_read2_b32 v[90:91], v64 offset1:32
	ds_read2_b32 v[84:85], v64 offset0:64 offset1:96
	v_add_u32_e32 v65, 0x400, v64
	ds_read2_b32 v[94:95], v65 offset1:32
	ds_read2_b32 v[92:93], v65 offset0:64 offset1:96
	v_add_u32_e32 v65, 0x800, v64
	ds_read2_b32 v[102:103], v65 offset1:32
	ds_read2_b32 v[122:123], v65 offset0:64 offset1:96
	s_waitcnt lgkmcnt(4)
	v_pk_mul_f32 v[84:85], v[200:201], v[84:85]
	v_add_u32_e32 v65, 0xc00, v64
	v_pk_fma_f32 v[84:85], v[50:51], v[70:71], v[84:85] op_sel_hi:[1,0,1] neg_lo:[0,0,1] neg_hi:[0,0,1]
	v_pk_mul_f32 v[50:51], v[200:201], v[90:91]
	ds_read2_b32 v[124:125], v65 offset1:32
	ds_read2_b32 v[126:127], v65 offset0:64 offset1:96
	v_pk_fma_f32 v[90:91], v[48:49], v[70:71], v[50:51] op_sel_hi:[1,0,1] neg_lo:[0,0,1] neg_hi:[0,0,1]
	v_add_u32_e32 v65, 0x1000, v64
	v_mul_f32_e32 v48, v91, v91
	v_pk_fma_f32 v[48:49], v[90:91], v[90:91], v[48:49] op_sel_hi:[1,1,0]
	ds_read2_b32 v[128:129], v65 offset1:32
	s_waitcnt vmcnt(1)
	ds_read2_b32 v[130:131], v65 offset0:64 offset1:96
	v_add_u32_e32 v65, 0x1400, v64
	v_pk_fma_f32 v[48:49], v[84:85], v[84:85], v[48:49]
	v_mul_f32_e32 v50, v85, v85
	ds_read2_b32 v[132:133], v65 offset1:32
	s_waitcnt vmcnt(0)
	ds_read2_b32 v[134:135], v65 offset0:64 offset1:96
	v_add_u32_e32 v65, 0x1800, v64
	v_pk_add_f32 v[48:49], v[48:49], v[50:51] op_sel_hi:[1,0]
	s_waitcnt lgkmcnt(8)
	v_pk_mul_f32 v[50:51], v[200:201], v[92:93]
	ds_read2_b32 v[120:121], v65 offset1:32
	ds_read2_b32 v[136:137], v65 offset0:64 offset1:96
	v_add_u32_e32 v65, 0x1c00, v64
	v_pk_fma_f32 v[92:93], v[54:55], v[70:71], v[50:51] op_sel_hi:[1,0,1] neg_lo:[0,0,1] neg_hi:[0,0,1]
	v_pk_mul_f32 v[50:51], v[200:201], v[94:95]
	ds_read2_b32 v[116:117], v65 offset1:32
	ds_read2_b32 v[118:119], v65 offset0:64 offset1:96
	v_add_u32_e32 v65, 0x2000, v64
	v_pk_fma_f32 v[100:101], v[52:53], v[70:71], v[50:51] op_sel_hi:[1,0,1] neg_lo:[0,0,1] neg_hi:[0,0,1]
	ds_read2_b32 v[110:111], v65 offset1:32
	ds_read2_b32 v[114:115], v65 offset0:64 offset1:96
	v_add_u32_e32 v65, 0x2400, v64
	v_pk_fma_f32 v[48:49], v[100:101], v[100:101], v[48:49]
	v_mul_f32_e32 v50, v101, v101
	ds_read2_b32 v[106:107], v65 offset1:32
	ds_read2_b32 v[108:109], v65 offset0:64 offset1:96
	v_add_u32_e32 v65, 0x2800, v64
	v_pk_add_f32 v[48:49], v[48:49], v[50:51] op_sel_hi:[1,0]
	ds_read2_b32 v[98:99], v65 offset1:32
	ds_read2_b32 v[104:105], v65 offset0:64 offset1:96
	v_add_u32_e32 v65, 0x2c00, v64
	v_pk_fma_f32 v[48:49], v[92:93], v[92:93], v[48:49]
	v_mul_f32_e32 v50, v93, v93
	ds_read2_b32 v[88:89], v65 offset1:32
	ds_read2_b32 v[96:97], v65 offset0:64 offset1:96
	v_add_u32_e32 v65, 0x3000, v64
	v_pk_add_f32 v[48:49], v[48:49], v[50:51] op_sel_hi:[1,0]
	s_waitcnt lgkmcnt(14)
	v_pk_mul_f32 v[50:51], v[200:201], v[122:123]
	ds_read2_b32 v[82:83], v65 offset1:32
	ds_read2_b32 v[86:87], v65 offset0:64 offset1:96
	v_add_u32_e32 v65, 0x3400, v64
	v_pk_fma_f32 v[94:95], v[58:59], v[70:71], v[50:51] op_sel_hi:[1,0,1] neg_lo:[0,0,1] neg_hi:[0,0,1]
	v_pk_mul_f32 v[50:51], v[200:201], v[102:103]
	ds_read2_b32 v[78:79], v65 offset1:32
	ds_read2_b32 v[80:81], v65 offset0:64 offset1:96
	v_add_u32_e32 v65, 0x3800, v64
	v_add_u32_e32 v64, 0x3c00, v64
	v_pk_fma_f32 v[102:103], v[56:57], v[70:71], v[50:51] op_sel_hi:[1,0,1] neg_lo:[0,0,1] neg_hi:[0,0,1]
	ds_read2_b32 v[72:73], v65 offset1:32
	ds_read2_b32 v[76:77], v65 offset0:64 offset1:96
	ds_read2_b32 v[74:75], v64 offset1:32
	ds_read2_b32 v[64:65], v64 offset0:64 offset1:96
	v_pk_fma_f32 v[48:49], v[102:103], v[102:103], v[48:49]
	v_mul_f32_e32 v50, v103, v103
	v_pk_add_f32 v[48:49], v[48:49], v[50:51] op_sel_hi:[1,0]
	v_mul_f32_e32 v50, v95, v95
	v_pk_fma_f32 v[48:49], v[94:95], v[94:95], v[48:49]
	s_waitcnt lgkmcnt(0)
	v_pk_mul_f32 v[64:65], v[200:201], v[64:65]
	v_pk_add_f32 v[48:49], v[48:49], v[50:51] op_sel_hi:[1,0]
	v_pk_mul_f32 v[50:51], v[200:201], v[126:127]
	v_pk_fma_f32 v[68:69], v[14:15], v[70:71], v[64:65] op_sel_hi:[1,0,1] neg_lo:[0,0,1] neg_hi:[0,0,1]
	v_pk_fma_f32 v[58:59], v[62:63], v[70:71], v[50:51] op_sel_hi:[1,0,1] neg_lo:[0,0,1] neg_hi:[0,0,1]
	v_pk_mul_f32 v[50:51], v[200:201], v[124:125]
	v_lshlrev_b64 v[14:15], 11, v[202:203]
	v_pk_fma_f32 v[62:63], v[60:61], v[70:71], v[50:51] op_sel_hi:[1,0,1] neg_lo:[0,0,1] neg_hi:[0,0,1]
	v_lshl_add_u64 v[14:15], s[48:49], 0, v[14:15]
	v_pk_fma_f32 v[48:49], v[62:63], v[62:63], v[48:49]
	v_mul_f32_e32 v50, v63, v63
	s_lshl_b32 s58, s18, 8
	v_pk_add_f32 v[48:49], v[48:49], v[50:51] op_sel_hi:[1,0]
	v_lshl_add_u64 v[14:15], v[14:15], 0, s[58:59]
	v_lshlrev_b32_e32 v64, 3, v226
	v_mov_b32_e32 v65, v113
	v_pk_fma_f32 v[48:49], v[58:59], v[58:59], v[48:49]
	v_mul_f32_e32 v50, v59, v59
	v_lshl_add_u64 v[14:15], v[14:15], 0, v[64:65]
	global_load_dwordx4 v[64:67], v112, s[2:3]
	global_load_dwordx4 v[148:151], v112, s[2:3] offset:32
	global_load_dwordx4 v[152:155], v112, s[2:3] offset:64
	global_load_dwordx4 v[156:159], v112, s[2:3] offset:96
	global_load_dwordx4 v[160:163], v112, s[2:3] offset:128
	global_load_dwordx4 v[164:167], v112, s[2:3] offset:160
	global_load_dwordx4 v[168:171], v112, s[2:3] offset:192
	global_load_dwordx4 v[176:179], v112, s[2:3] offset:224
	global_load_dwordx4 v[184:187], v112, s[2:3] offset:256
	global_load_dwordx4 v[204:207], v112, s[2:3] offset:288
	global_load_dwordx4 v[208:211], v112, s[2:3] offset:320
	global_load_dwordx4 v[232:235], v112, s[2:3] offset:352
	global_load_dwordx4 v[236:239], v112, s[2:3] offset:384
	global_load_dwordx4 v[240:243], v112, s[2:3] offset:416
; __device__ __forceinline__ float half_swap_sum(float v) { auto rr = __builtin_amdgcn_permlane32_swap(__float_as_uint(v), __float_as_uint(v), false, false); return __uint_as_float(rr[0]) + __uint_as_float(rr[1]); }
; __device__ __forceinline__ void attn_item(LAS unsigned char* lds, const bf16_t* Q, const bf16_t* Kb, const bf16_t* VT, bf16_t* aout, const float* subg, float lam, float omli, float kbound, int head, int qb) {
;     ...
;             for (int i = 0; i < 16; ++i) { const float o = O[e][i] * inv - lam * X[(qt * 128 + 32 * e + (i & 3) + 8 * (i >> 2) + 4 * hh) * 32 + r]; O[e][i] = o; ss += o * o; }
;         ss = half_swap_sum(ss);
;         const float rn = __builtin_amdgcn_rsqf(ss * (1.f / 128.f) + EPS) * omli;
;         bf16_t* ap = aout + (size_t)q * 1024 + head * 128 + 4 * hh;
; #pragma unroll
;         for (int e = 0; e < 4; ++e)
; #pragma unroll
;             for (int g4 = 0; g4 < 4; ++g4) { const int e0 = 32 * e + 8 * g4; const f32x4 sg = *(const f32x4*)(subg + e0 + 4 * hh);
	global_load_dwordx4 v[244:247], v112, s[2:3] offset:448
	global_load_dwordx4 v[248:251], v112, s[2:3] offset:480
	v_pk_add_f32 v[48:49], v[48:49], v[50:51] op_sel_hi:[1,0]
	v_pk_mul_f32 v[50:51], v[200:201], v[130:131]
	s_nop 0
	v_pk_fma_f32 v[54:55], v[34:35], v[70:71], v[50:51] op_sel_hi:[1,0,1] neg_lo:[0,0,1] neg_hi:[0,0,1]
	v_pk_mul_f32 v[34:35], v[200:201], v[128:129]
	s_nop 0
	v_pk_fma_f32 v[60:61], v[32:33], v[70:71], v[34:35] op_sel_hi:[1,0,1] neg_lo:[0,0,1] neg_hi:[0,0,1]
	s_nop 0
	v_pk_fma_f32 v[32:33], v[60:61], v[60:61], v[48:49]
	v_mul_f32_e32 v34, v61, v61
	v_pk_add_f32 v[32:33], v[32:33], v[34:35] op_sel_hi:[1,0]
	v_mul_f32_e32 v34, v55, v55
	v_pk_fma_f32 v[32:33], v[54:55], v[54:55], v[32:33]
	s_nop 0
	v_pk_add_f32 v[32:33], v[32:33], v[34:35] op_sel_hi:[1,0]
	v_pk_mul_f32 v[34:35], v[200:201], v[134:135]
	s_nop 0
	v_pk_fma_f32 v[50:51], v[38:39], v[70:71], v[34:35] op_sel_hi:[1,0,1] neg_lo:[0,0,1] neg_hi:[0,0,1]
	v_pk_mul_f32 v[34:35], v[200:201], v[132:133]
	s_nop 0
	v_pk_fma_f32 v[56:57], v[36:37], v[70:71], v[34:35] op_sel_hi:[1,0,1] neg_lo:[0,0,1] neg_hi:[0,0,1]
	s_nop 0
	v_pk_fma_f32 v[32:33], v[56:57], v[56:57], v[32:33]
	v_mul_f32_e32 v34, v57, v57
	v_pk_add_f32 v[32:33], v[32:33], v[34:35] op_sel_hi:[1,0]
	v_mul_f32_e32 v34, v51, v51
	v_pk_fma_f32 v[32:33], v[50:51], v[50:51], v[32:33]
	s_nop 0
	v_pk_add_f32 v[32:33], v[32:33], v[34:35] op_sel_hi:[1,0]
	v_pk_mul_f32 v[34:35], v[200:201], v[136:137]
	s_nop 0
	v_pk_fma_f32 v[48:49], v[42:43], v[70:71], v[34:35] op_sel_hi:[1,0,1] neg_lo:[0,0,1] neg_hi:[0,0,1]
	v_pk_mul_f32 v[34:35], v[200:201], v[120:121]
	s_nop 0
	v_pk_fma_f32 v[52:53], v[40:41], v[70:71], v[34:35] op_sel_hi:[1,0,1] neg_lo:[0,0,1] neg_hi:[0,0,1]
	s_nop 0
	v_pk_fma_f32 v[32:33], v[52:53], v[52:53], v[32:33]
	v_mul_f32_e32 v34, v53, v53
	v_pk_add_f32 v[32:33], v[32:33], v[34:35] op_sel_hi:[1,0]
	v_mul_f32_e32 v34, v49, v49
	v_pk_fma_f32 v[32:33], v[48:49], v[48:49], v[32:33]
	s_nop 0
	v_pk_add_f32 v[32:33], v[32:33], v[34:35] op_sel_hi:[1,0]
	v_pk_mul_f32 v[34:35], v[200:201], v[118:119]
	s_nop 0
	v_pk_fma_f32 v[40:41], v[46:47], v[70:71], v[34:35] op_sel_hi:[1,0,1] neg_lo:[0,0,1] neg_hi:[0,0,1]
	v_pk_mul_f32 v[34:35], v[200:201], v[116:117]
	s_nop 0
	v_pk_fma_f32 v[44:45], v[44:45], v[70:71], v[34:35] op_sel_hi:[1,0,1] neg_lo:[0,0,1] neg_hi:[0,0,1]
	s_nop 0
	v_pk_fma_f32 v[32:33], v[44:45], v[44:45], v[32:33]
	v_mul_f32_e32 v34, v45, v45
	v_pk_add_f32 v[32:33], v[32:33], v[34:35] op_sel_hi:[1,0]
	v_mul_f32_e32 v34, v41, v41
	v_pk_fma_f32 v[32:33], v[40:41], v[40:41], v[32:33]
	s_nop 0
	v_pk_add_f32 v[32:33], v[32:33], v[34:35] op_sel_hi:[1,0]
	v_pk_mul_f32 v[34:35], v[200:201], v[114:115]
	s_nop 0
	v_pk_fma_f32 v[36:37], v[18:19], v[70:71], v[34:35] op_sel_hi:[1,0,1] neg_lo:[0,0,1] neg_hi:[0,0,1]
	v_pk_mul_f32 v[18:19], v[200:201], v[110:111]
	s_nop 0
	v_pk_fma_f32 v[42:43], v[16:17], v[70:71], v[18:19] op_sel_hi:[1,0,1] neg_lo:[0,0,1] neg_hi:[0,0,1]
	s_nop 0
	v_pk_fma_f32 v[16:17], v[42:43], v[42:43], v[32:33]
	v_mul_f32_e32 v18, v43, v43
	v_pk_add_f32 v[16:17], v[16:17], v[18:19] op_sel_hi:[1,0]
	v_mul_f32_e32 v18, v37, v37
	v_pk_fma_f32 v[16:17], v[36:37], v[36:37], v[16:17]
	s_nop 0
	v_pk_add_f32 v[16:17], v[16:17], v[18:19] op_sel_hi:[1,0]
	v_pk_mul_f32 v[18:19], v[200:201], v[108:109]
	s_nop 0
	v_pk_fma_f32 v[32:33], v[22:23], v[70:71], v[18:19] op_sel_hi:[1,0,1] neg_lo:[0,0,1] neg_hi:[0,0,1]
	v_pk_mul_f32 v[18:19], v[200:201], v[106:107]
	s_nop 0
	v_pk_fma_f32 v[38:39], v[20:21], v[70:71], v[18:19] op_sel_hi:[1,0,1] neg_lo:[0,0,1] neg_hi:[0,0,1]
	s_nop 0
	v_pk_fma_f32 v[16:17], v[38:39], v[38:39], v[16:17]
	v_mul_f32_e32 v18, v39, v39
	v_pk_add_f32 v[16:17], v[16:17], v[18:19] op_sel_hi:[1,0]
	v_mul_f32_e32 v18, v33, v33
	v_pk_fma_f32 v[16:17], v[32:33], v[32:33], v[16:17]
	s_nop 0
	v_pk_add_f32 v[16:17], v[16:17], v[18:19] op_sel_hi:[1,0]
	v_pk_mul_f32 v[18:19], v[200:201], v[104:105]
	s_nop 0
	v_pk_fma_f32 v[26:27], v[26:27], v[70:71], v[18:19] op_sel_hi:[1,0,1] neg_lo:[0,0,1] neg_hi:[0,0,1]
	v_pk_mul_f32 v[18:19], v[200:201], v[98:99]
	s_nop 0
	v_pk_fma_f32 v[34:35], v[24:25], v[70:71], v[18:19] op_sel_hi:[1,0,1] neg_lo:[0,0,1] neg_hi:[0,0,1]
	s_nop 0
	v_pk_fma_f32 v[16:17], v[34:35], v[34:35], v[16:17]
	v_mul_f32_e32 v18, v35, v35
	v_pk_add_f32 v[16:17], v[16:17], v[18:19] op_sel_hi:[1,0]
	v_mul_f32_e32 v18, v27, v27
	v_pk_fma_f32 v[16:17], v[26:27], v[26:27], v[16:17]
	s_nop 0
	v_pk_add_f32 v[16:17], v[16:17], v[18:19] op_sel_hi:[1,0]
	v_pk_mul_f32 v[18:19], v[200:201], v[96:97]
	s_nop 0
	v_pk_fma_f32 v[20:21], v[30:31], v[70:71], v[18:19] op_sel_hi:[1,0,1] neg_lo:[0,0,1] neg_hi:[0,0,1]
	v_pk_mul_f32 v[18:19], v[200:201], v[88:89]
	s_nop 0
	v_pk_fma_f32 v[24:25], v[28:29], v[70:71], v[18:19] op_sel_hi:[1,0,1] neg_lo:[0,0,1] neg_hi:[0,0,1]
	s_nop 0
	v_pk_fma_f32 v[16:17], v[24:25], v[24:25], v[16:17]
	v_mul_f32_e32 v18, v25, v25
	v_pk_add_f32 v[16:17], v[16:17], v[18:19] op_sel_hi:[1,0]
	v_mul_f32_e32 v18, v21, v21
	v_pk_fma_f32 v[16:17], v[20:21], v[20:21], v[16:17]
	s_nop 0
	v_pk_add_f32 v[18:19], v[16:17], v[18:19] op_sel_hi:[1,0]
	v_pk_mul_f32 v[16:17], v[200:201], v[86:87]
	s_nop 0
	v_pk_fma_f32 v[16:17], v[2:3], v[70:71], v[16:17] op_sel_hi:[1,0,1] neg_lo:[0,0,1] neg_hi:[0,0,1]
	v_pk_mul_f32 v[2:3], v[200:201], v[82:83]
	s_nop 0
	v_pk_fma_f32 v[22:23], v[0:1], v[70:71], v[2:3] op_sel_hi:[1,0,1] neg_lo:[0,0,1] neg_hi:[0,0,1]
	s_nop 0
	v_pk_fma_f32 v[0:1], v[22:23], v[22:23], v[18:19]
	v_mul_f32_e32 v2, v23, v23
	v_pk_add_f32 v[0:1], v[0:1], v[2:3] op_sel_hi:[1,0]
	v_mul_f32_e32 v2, v17, v17
	v_pk_fma_f32 v[0:1], v[16:17], v[16:17], v[0:1]
	s_nop 0
	v_pk_add_f32 v[0:1], v[0:1], v[2:3] op_sel_hi:[1,0]
; __device__ __forceinline__ unsigned pk2(float lo, float hi) { f32x2 v = {lo, hi}; bf16x2_t b = __builtin_convertvector(v, bf16x2_t); return __builtin_bit_cast(unsigned, b); }
; __device__ __forceinline__ float half_swap_sum(float v) { auto rr = __builtin_amdgcn_permlane32_swap(__float_as_uint(v), __float_as_uint(v), false, false); return __uint_as_float(rr[0]) + __uint_as_float(rr[1]); }
; __device__ __forceinline__ void attn_item(LAS unsigned char* lds, const bf16_t* Q, const bf16_t* Kb, const bf16_t* VT, bf16_t* aout, const float* subg, float lam, float omli, float kbound, int head, int qb) {
;     ...
;         ss = half_swap_sum(ss);
;         const float rn = __builtin_amdgcn_rsqf(ss * (1.f / 128.f) + EPS) * omli;
;         bf16_t* ap = aout + (size_t)q * 1024 + head * 128 + 4 * hh;
; #pragma unroll
;         for (int e = 0; e < 4; ++e)
; #pragma unroll
;             for (int g4 = 0; g4 < 4; ++g4) { const int e0 = 32 * e + 8 * g4; const f32x4 sg = *(const f32x4*)(subg + e0 + 4 * hh);
;                 u32x2 w; w.x = pk2(O[e][4 * g4 + 0] * rn * sg[0], O[e][4 * g4 + 1] * rn * sg[1]); w.y = pk2(O[e][4 * g4 + 2] * rn * sg[2], O[e][4 * g4 + 3] * rn * sg[3]);
;                 *(u32x2*)(ap + e0) = w; }
	v_pk_mul_f32 v[2:3], v[200:201], v[80:81]
	s_nop 0
	v_pk_fma_f32 v[6:7], v[6:7], v[70:71], v[2:3] op_sel_hi:[1,0,1] neg_lo:[0,0,1] neg_hi:[0,0,1]
	v_pk_mul_f32 v[2:3], v[200:201], v[78:79]
	s_nop 0
	v_pk_fma_f32 v[18:19], v[4:5], v[70:71], v[2:3] op_sel_hi:[1,0,1] neg_lo:[0,0,1] neg_hi:[0,0,1]
	v_pk_mul_f32 v[4:5], v[200:201], v[72:73]
	v_pk_fma_f32 v[0:1], v[18:19], v[18:19], v[0:1]
	v_mul_f32_e32 v2, v19, v19
	v_pk_add_f32 v[0:1], v[0:1], v[2:3] op_sel_hi:[1,0]
	v_mul_f32_e32 v2, v7, v7
	v_pk_fma_f32 v[0:1], v[6:7], v[6:7], v[0:1]
	v_pk_fma_f32 v[4:5], v[8:9], v[70:71], v[4:5] op_sel_hi:[1,0,1] neg_lo:[0,0,1] neg_hi:[0,0,1]
	v_pk_add_f32 v[2:3], v[0:1], v[2:3] op_sel_hi:[1,0]
	v_pk_mul_f32 v[0:1], v[200:201], v[76:77]
	v_pk_fma_f32 v[2:3], v[4:5], v[4:5], v[2:3]
	v_mul_f32_e32 v8, v5, v5
	v_pk_fma_f32 v[0:1], v[10:11], v[70:71], v[0:1] op_sel_hi:[1,0,1] neg_lo:[0,0,1] neg_hi:[0,0,1]
	v_pk_add_f32 v[2:3], v[2:3], v[8:9] op_sel_hi:[1,0]
	v_mul_f32_e32 v8, v1, v1
	v_pk_fma_f32 v[2:3], v[0:1], v[0:1], v[2:3]
	s_nop 0
	v_pk_add_f32 v[8:9], v[2:3], v[8:9] op_sel_hi:[1,0]
	v_pk_mul_f32 v[2:3], v[200:201], v[74:75]
	s_nop 0
	v_pk_fma_f32 v[2:3], v[12:13], v[70:71], v[2:3] op_sel_hi:[1,0,1] neg_lo:[0,0,1] neg_hi:[0,0,1]
	s_nop 0
	v_pk_fma_f32 v[8:9], v[2:3], v[2:3], v[8:9]
	v_mul_f32_e32 v10, v3, v3
	v_pk_add_f32 v[8:9], v[8:9], v[10:11] op_sel_hi:[1,0]
	v_mul_f32_e32 v10, v69, v69
	v_pk_fma_f32 v[8:9], v[68:69], v[68:69], v[8:9]
	s_nop 0
	v_pk_add_f32 v[8:9], v[8:9], v[10:11] op_sel_hi:[1,0]
	s_nop 0
	v_mov_b32_e32 v9, v8
	s_nop 1
	v_permlane32_swap_b32_e32 v8, v9
	v_add_f32_e32 v8, v8, v9
	v_fmamk_f32 v8, v8, 0x3c000000, v217
	v_rsq_f32_e32 v8, v8
	s_nop 0
	v_mul_f32_e32 v8, v224, v8
	v_pk_mul_f32 v[10:11], v[90:91], v[8:9] op_sel_hi:[1,0]
	v_pk_mul_f32 v[12:13], v[84:85], v[8:9] op_sel_hi:[1,0]
	s_waitcnt vmcnt(0)
	v_pk_mul_f32 v[10:11], v[64:65], v[10:11]
	v_pk_mul_f32 v[12:13], v[66:67], v[12:13]
	v_cvt_pk_bf16_f32 v10, v10, v11
	v_cvt_pk_bf16_f32 v11, v12, v13
	global_store_dwordx2 v[14:15], v[10:11], off
	s_nop 1
	v_pk_mul_f32 v[28:29], v[100:101], v[8:9] op_sel_hi:[1,0]
	v_pk_mul_f32 v[26:27], v[26:27], v[8:9] op_sel_hi:[1,0]
	v_pk_mul_f32 v[24:25], v[24:25], v[8:9] op_sel_hi:[1,0]
	v_pk_mul_f32 v[20:21], v[20:21], v[8:9] op_sel_hi:[1,0]
	v_pk_mul_f32 v[16:17], v[16:17], v[8:9] op_sel_hi:[1,0]
	v_pk_mul_f32 v[6:7], v[6:7], v[8:9] op_sel_hi:[1,0]
	v_pk_mul_f32 v[4:5], v[4:5], v[8:9] op_sel_hi:[1,0]
	v_pk_mul_f32 v[0:1], v[0:1], v[8:9] op_sel_hi:[1,0]
	v_pk_mul_f32 v[10:11], v[148:149], v[28:29]
	v_pk_mul_f32 v[28:29], v[92:93], v[8:9] op_sel_hi:[1,0]
	v_cvt_pk_bf16_f32 v10, v10, v11
	v_pk_mul_f32 v[12:13], v[150:151], v[28:29]
	v_pk_mul_f32 v[28:29], v[102:103], v[8:9] op_sel_hi:[1,0]
	v_cvt_pk_bf16_f32 v11, v12, v13
	global_store_dwordx2 v[14:15], v[10:11], off offset:16
	s_nop 1
	v_pk_mul_f32 v[10:11], v[152:153], v[28:29]
	v_pk_mul_f32 v[28:29], v[94:95], v[8:9] op_sel_hi:[1,0]
	v_cvt_pk_bf16_f32 v10, v10, v11
	v_pk_mul_f32 v[12:13], v[154:155], v[28:29]
	v_pk_mul_f32 v[28:29], v[62:63], v[8:9] op_sel_hi:[1,0]
	v_cvt_pk_bf16_f32 v11, v12, v13
	global_store_dwordx2 v[14:15], v[10:11], off offset:32
	s_nop 1
	v_pk_mul_f32 v[10:11], v[156:157], v[28:29]
	v_pk_mul_f32 v[28:29], v[58:59], v[8:9] op_sel_hi:[1,0]
	v_cvt_pk_bf16_f32 v10, v10, v11
	v_pk_mul_f32 v[12:13], v[158:159], v[28:29]
	v_pk_mul_f32 v[28:29], v[60:61], v[8:9] op_sel_hi:[1,0]
	v_cvt_pk_bf16_f32 v11, v12, v13
	global_store_dwordx2 v[14:15], v[10:11], off offset:48
	s_nop 1
	v_pk_mul_f32 v[10:11], v[28:29], v[160:161]
	v_pk_mul_f32 v[28:29], v[54:55], v[8:9] op_sel_hi:[1,0]
	v_cvt_pk_bf16_f32 v10, v10, v11
	v_pk_mul_f32 v[12:13], v[28:29], v[162:163]
	v_pk_mul_f32 v[28:29], v[56:57], v[8:9] op_sel_hi:[1,0]
	v_cvt_pk_bf16_f32 v11, v12, v13
	global_store_dwordx2 v[14:15], v[10:11], off offset:64
	s_nop 1
	v_pk_mul_f32 v[10:11], v[28:29], v[164:165]
	v_pk_mul_f32 v[28:29], v[50:51], v[8:9] op_sel_hi:[1,0]
	v_cvt_pk_bf16_f32 v10, v10, v11
	v_pk_mul_f32 v[12:13], v[28:29], v[166:167]
	v_pk_mul_f32 v[28:29], v[52:53], v[8:9] op_sel_hi:[1,0]
	v_cvt_pk_bf16_f32 v11, v12, v13
	global_store_dwordx2 v[14:15], v[10:11], off offset:80
	s_nop 1
	v_pk_mul_f32 v[10:11], v[28:29], v[168:169]
	v_pk_mul_f32 v[28:29], v[48:49], v[8:9] op_sel_hi:[1,0]
	v_cvt_pk_bf16_f32 v10, v10, v11
	v_pk_mul_f32 v[12:13], v[28:29], v[170:171]
	v_pk_mul_f32 v[28:29], v[44:45], v[8:9] op_sel_hi:[1,0]
	v_cvt_pk_bf16_f32 v11, v12, v13
	global_store_dwordx2 v[14:15], v[10:11], off offset:96
	s_nop 1
	v_pk_mul_f32 v[10:11], v[28:29], v[176:177]
	v_pk_mul_f32 v[28:29], v[40:41], v[8:9] op_sel_hi:[1,0]
	v_cvt_pk_bf16_f32 v10, v10, v11
	v_pk_mul_f32 v[12:13], v[28:29], v[178:179]
	v_pk_mul_f32 v[28:29], v[42:43], v[8:9] op_sel_hi:[1,0]
	v_cvt_pk_bf16_f32 v11, v12, v13
	global_store_dwordx2 v[14:15], v[10:11], off offset:112
	s_nop 1
	v_pk_mul_f32 v[10:11], v[28:29], v[184:185]
	v_pk_mul_f32 v[28:29], v[36:37], v[8:9] op_sel_hi:[1,0]
	v_cvt_pk_bf16_f32 v10, v10, v11
	v_pk_mul_f32 v[12:13], v[28:29], v[186:187]
	v_pk_mul_f32 v[28:29], v[38:39], v[8:9] op_sel_hi:[1,0]
	v_cvt_pk_bf16_f32 v11, v12, v13
	global_store_dwordx2 v[14:15], v[10:11], off offset:128
	s_nop 1
	v_pk_mul_f32 v[10:11], v[28:29], v[204:205]
	v_pk_mul_f32 v[28:29], v[32:33], v[8:9] op_sel_hi:[1,0]
	v_cvt_pk_bf16_f32 v10, v10, v11
	v_pk_mul_f32 v[12:13], v[28:29], v[206:207]
	v_pk_mul_f32 v[28:29], v[34:35], v[8:9] op_sel_hi:[1,0]
	v_cvt_pk_bf16_f32 v11, v12, v13
	global_store_dwordx2 v[14:15], v[10:11], off offset:144
	s_nop 1
	v_pk_mul_f32 v[10:11], v[28:29], v[208:209]
	v_pk_mul_f32 v[12:13], v[26:27], v[210:211]
	v_cvt_pk_bf16_f32 v10, v10, v11
	v_cvt_pk_bf16_f32 v11, v12, v13
	global_store_dwordx2 v[14:15], v[10:11], off offset:160
	s_nop 1
	v_pk_mul_f32 v[10:11], v[24:25], v[232:233]
	v_pk_mul_f32 v[12:13], v[20:21], v[234:235]
	v_cvt_pk_bf16_f32 v10, v10, v11
	v_cvt_pk_bf16_f32 v11, v12, v13
	global_store_dwordx2 v[14:15], v[10:11], off offset:176
	s_nop 1
	v_pk_mul_f32 v[20:21], v[22:23], v[8:9] op_sel_hi:[1,0]
	v_pk_mul_f32 v[12:13], v[16:17], v[238:239]
	v_pk_mul_f32 v[10:11], v[20:21], v[236:237]
	v_pk_mul_f32 v[16:17], v[18:19], v[8:9] op_sel_hi:[1,0]
	v_cvt_pk_bf16_f32 v10, v10, v11
	v_cvt_pk_bf16_f32 v11, v12, v13
	global_store_dwordx2 v[14:15], v[10:11], off offset:192
	s_nop 1
	v_pk_mul_f32 v[10:11], v[16:17], v[240:241]
	v_pk_mul_f32 v[6:7], v[6:7], v[242:243]
	v_cvt_pk_bf16_f32 v10, v10, v11
	v_cvt_pk_bf16_f32 v11, v6, v7
	global_store_dwordx2 v[14:15], v[10:11], off offset:208
	s_nop 1
	v_pk_mul_f32 v[4:5], v[4:5], v[244:245]
	v_pk_mul_f32 v[0:1], v[0:1], v[246:247]
	v_cvt_pk_bf16_f32 v4, v4, v5
	v_cvt_pk_bf16_f32 v5, v0, v1
	global_store_dwordx2 v[14:15], v[4:5], off offset:224
	s_nop 1
	v_pk_mul_f32 v[0:1], v[2:3], v[8:9] op_sel_hi:[1,0]
	v_pk_mul_f32 v[2:3], v[68:69], v[8:9] op_sel_hi:[1,0]
	v_pk_mul_f32 v[0:1], v[0:1], v[248:249]
	v_pk_mul_f32 v[2:3], v[2:3], v[250:251]
	v_cvt_pk_bf16_f32 v0, v0, v1
	v_cvt_pk_bf16_f32 v1, v2, v3
	global_store_dwordx2 v[14:15], v[0:1], off offset:240

; __device__ __forceinline__ float half_swap_sum(float v) { auto rr = __builtin_amdgcn_permlane32_swap(__float_as_uint(v), __float_as_uint(v), false, false); return __uint_as_float(rr[0]) + __uint_as_float(rr[1]); }
; __device__ __forceinline__ void attn_item(LAS unsigned char* lds, const bf16_t* Q, const bf16_t* Kb, const bf16_t* VT, bf16_t* aout, const float* subg, float lam, float omli, float kbound, int head, int qb) {
;     ...
;     if (comp == 0) {
;         float ss = 0.f;
; #pragma unroll
;         for (int e = 0; e < 4; ++e)
; #pragma unroll
;             for (int i = 0; i < 16; ++i) { const float o = O[e][i] * inv - lam * X[(qt * 128 + 32 * e + (i & 3) + 8 * (i >> 2) + 4 * hh) * 32 + r]; O[e][i] = o; ss += o * o; }
;         ss = half_swap_sum(ss);
;         const float rn = __builtin_amdgcn_rsqf(ss * (1.f / 128.f) + EPS) * omli;
;         bf16_t* ap = aout + (size_t)q * 1024 + head * 128 + 4 * hh;
; #pragma unroll
;         for (int e = 0; e < 4; ++e)
; #pragma unroll
;             for (int g4 = 0; g4 < 4; ++g4) { const int e0 = 32 * e + 8 * g4; const f32x4 sg = *(const f32x4*)(subg + e0 + 4 * hh);
.LBB0_366:
	s_andn2_b64 vcc, exec, s[4:5]
	s_waitcnt lgkmcnt(0)
	s_barrier
	s_cbranch_vccnz .LBB0_291
	s_lshl_b32 s0, s0, 14
	v_add3_u32 v64, v65, v64, s0
	ds_read2_b32 v[90:91], v64 offset1:32
	ds_read2_b32 v[84:85], v64 offset0:64 offset1:96
	v_add_u32_e32 v65, 0x400, v64
	ds_read2_b32 v[94:95], v65 offset1:32
	ds_read2_b32 v[92:93], v65 offset0:64 offset1:96
	v_add_u32_e32 v65, 0x800, v64
	ds_read2_b32 v[102:103], v65 offset1:32
	ds_read2_b32 v[122:123], v65 offset0:64 offset1:96
	s_waitcnt lgkmcnt(4)
	v_pk_mul_f32 v[84:85], v[200:201], v[84:85]
	v_add_u32_e32 v65, 0xc00, v64
	v_pk_fma_f32 v[84:85], v[50:51], v[70:71], v[84:85] op_sel_hi:[1,0,1] neg_lo:[0,0,1] neg_hi:[0,0,1]
	v_pk_mul_f32 v[50:51], v[200:201], v[90:91]
	ds_read2_b32 v[124:125], v65 offset1:32
	ds_read2_b32 v[126:127], v65 offset0:64 offset1:96
	v_pk_fma_f32 v[90:91], v[48:49], v[70:71], v[50:51] op_sel_hi:[1,0,1] neg_lo:[0,0,1] neg_hi:[0,0,1]
	v_add_u32_e32 v65, 0x1000, v64
	v_mul_f32_e32 v48, v91, v91
	v_pk_fma_f32 v[48:49], v[90:91], v[90:91], v[48:49] op_sel_hi:[1,1,0]
	ds_read2_b32 v[128:129], v65 offset1:32
	s_waitcnt vmcnt(1)
	ds_read2_b32 v[130:131], v65 offset0:64 offset1:96
	v_add_u32_e32 v65, 0x1400, v64
	v_pk_fma_f32 v[48:49], v[84:85], v[84:85], v[48:49]
	v_mul_f32_e32 v50, v85, v85
	ds_read2_b32 v[132:133], v65 offset1:32
	s_waitcnt vmcnt(0)
	ds_read2_b32 v[134:135], v65 offset0:64 offset1:96
	v_add_u32_e32 v65, 0x1800, v64
	v_pk_add_f32 v[48:49], v[48:49], v[50:51] op_sel_hi:[1,0]
	s_waitcnt lgkmcnt(8)
	v_pk_mul_f32 v[50:51], v[200:201], v[92:93]
	ds_read2_b32 v[120:121], v65 offset1:32
	ds_read2_b32 v[136:137], v65 offset0:64 offset1:96
	v_add_u32_e32 v65, 0x1c00, v64
	v_pk_fma_f32 v[92:93], v[54:55], v[70:71], v[50:51] op_sel_hi:[1,0,1] neg_lo:[0,0,1] neg_hi:[0,0,1]
	v_pk_mul_f32 v[50:51], v[200:201], v[94:95]
	ds_read2_b32 v[116:117], v65 offset1:32
	ds_read2_b32 v[118:119], v65 offset0:64 offset1:96
	v_add_u32_e32 v65, 0x2000, v64
	v_pk_fma_f32 v[100:101], v[52:53], v[70:71], v[50:51] op_sel_hi:[1,0,1] neg_lo:[0,0,1] neg_hi:[0,0,1]
	ds_read2_b32 v[110:111], v65 offset1:32
	ds_read2_b32 v[114:115], v65 offset0:64 offset1:96
	v_add_u32_e32 v65, 0x2400, v64
	v_pk_fma_f32 v[48:49], v[100:101], v[100:101], v[48:49]
	v_mul_f32_e32 v50, v101, v101
	ds_read2_b32 v[106:107], v65 offset1:32
	ds_read2_b32 v[108:109], v65 offset0:64 offset1:96
	v_add_u32_e32 v65, 0x2800, v64
	v_pk_add_f32 v[48:49], v[48:49], v[50:51] op_sel_hi:[1,0]
	ds_read2_b32 v[98:99], v65 offset1:32
	ds_read2_b32 v[104:105], v65 offset0:64 offset1:96
	v_add_u32_e32 v65, 0x2c00, v64
	v_pk_fma_f32 v[48:49], v[92:93], v[92:93], v[48:49]
	v_mul_f32_e32 v50, v93, v93
	ds_read2_b32 v[88:89], v65 offset1:32
	ds_read2_b32 v[96:97], v65 offset0:64 offset1:96
	v_add_u32_e32 v65, 0x3000, v64
	v_pk_add_f32 v[48:49], v[48:49], v[50:51] op_sel_hi:[1,0]
	s_waitcnt lgkmcnt(14)
	v_pk_mul_f32 v[50:51], v[200:201], v[122:123]
	ds_read2_b32 v[82:83], v65 offset1:32
	ds_read2_b32 v[86:87], v65 offset0:64 offset1:96
	v_add_u32_e32 v65, 0x3400, v64
	v_pk_fma_f32 v[94:95], v[58:59], v[70:71], v[50:51] op_sel_hi:[1,0,1] neg_lo:[0,0,1] neg_hi:[0,0,1]
	v_pk_mul_f32 v[50:51], v[200:201], v[102:103]
	ds_read2_b32 v[78:79], v65 offset1:32
	ds_read2_b32 v[80:81], v65 offset0:64 offset1:96
	v_add_u32_e32 v65, 0x3800, v64
	v_add_u32_e32 v64, 0x3c00, v64
	v_pk_fma_f32 v[102:103], v[56:57], v[70:71], v[50:51] op_sel_hi:[1,0,1] neg_lo:[0,0,1] neg_hi:[0,0,1]
	ds_read2_b32 v[72:73], v65 offset1:32
	ds_read2_b32 v[76:77], v65 offset0:64 offset1:96
	ds_read2_b32 v[74:75], v64 offset1:32
	ds_read2_b32 v[64:65], v64 offset0:64 offset1:96
	v_pk_fma_f32 v[48:49], v[102:103], v[102:103], v[48:49]
	v_mul_f32_e32 v50, v103, v103
	v_pk_add_f32 v[48:49], v[48:49], v[50:51] op_sel_hi:[1,0]
	v_mul_f32_e32 v50, v95, v95
	v_pk_fma_f32 v[48:49], v[94:95], v[94:95], v[48:49]
	s_waitcnt lgkmcnt(0)
	v_pk_mul_f32 v[64:65], v[200:201], v[64:65]
	v_pk_add_f32 v[48:49], v[48:49], v[50:51] op_sel_hi:[1,0]
	v_pk_mul_f32 v[50:51], v[200:201], v[126:127]
	v_pk_fma_f32 v[68:69], v[14:15], v[70:71], v[64:65] op_sel_hi:[1,0,1] neg_lo:[0,0,1] neg_hi:[0,0,1]
	v_pk_fma_f32 v[58:59], v[62:63], v[70:71], v[50:51] op_sel_hi:[1,0,1] neg_lo:[0,0,1] neg_hi:[0,0,1]
	v_pk_mul_f32 v[50:51], v[200:201], v[124:125]
	v_lshlrev_b64 v[14:15], 11, v[202:203]
	v_pk_fma_f32 v[62:63], v[60:61], v[70:71], v[50:51] op_sel_hi:[1,0,1] neg_lo:[0,0,1] neg_hi:[0,0,1]
	v_lshl_add_u64 v[14:15], s[48:49], 0, v[14:15]
	v_pk_fma_f32 v[48:49], v[62:63], v[62:63], v[48:49]
	v_mul_f32_e32 v50, v63, v63
	s_lshl_b32 s58, s18, 8
	v_pk_add_f32 v[48:49], v[48:49], v[50:51] op_sel_hi:[1,0]
	v_lshl_add_u64 v[14:15], v[14:15], 0, s[58:59]
	v_lshlrev_b32_e32 v64, 3, v226
	v_mov_b32_e32 v65, v113
	v_pk_fma_f32 v[48:49], v[58:59], v[58:59], v[48:49]
	v_mul_f32_e32 v50, v59, v59
	v_lshl_add_u64 v[14:15], v[14:15], 0, v[64:65]
	global_load_dwordx4 v[64:67], v112, s[2:3]
	global_load_dwordx4 v[148:151], v112, s[2:3] offset:32
	global_load_dwordx4 v[152:155], v112, s[2:3] offset:64
	global_load_dwordx4 v[156:159], v112, s[2:3] offset:96
	global_load_dwordx4 v[160:163], v112, s[2:3] offset:128
	global_load_dwordx4 v[164:167], v112, s[2:3] offset:160
	global_load_dwordx4 v[168:171], v112, s[2:3] offset:192
	global_load_dwordx4 v[176:179], v112, s[2:3] offset:224
	global_load_dwordx4 v[184:187], v112, s[2:3] offset:256
	global_load_dwordx4 v[204:207], v112, s[2:3] offset:288
	global_load_dwordx4 v[208:211], v112, s[2:3] offset:320
	global_load_dwordx4 v[232:235], v112, s[2:3] offset:352
	global_load_dwordx4 v[236:239], v112, s[2:3] offset:384
	global_load_dwordx4 v[240:243], v112, s[2:3] offset:416
; __device__ __forceinline__ float half_swap_sum(float v) { auto rr = __builtin_amdgcn_permlane32_swap(__float_as_uint(v), __float_as_uint(v), false, false); return __uint_as_float(rr[0]) + __uint_as_float(rr[1]); }
; __device__ __forceinline__ void attn_item(LAS unsigned char* lds, const bf16_t* Q, const bf16_t* Kb, const bf16_t* VT, bf16_t* aout, const float* subg, float lam, float omli, float kbound, int head, int qb) {
;     ...
;             for (int i = 0; i < 16; ++i) { const float o = O[e][i] * inv - lam * X[(qt * 128 + 32 * e + (i & 3) + 8 * (i >> 2) + 4 * hh) * 32 + r]; O[e][i] = o; ss += o * o; }
;         ss = half_swap_sum(ss);
;         const float rn = __builtin_amdgcn_rsqf(ss * (1.f / 128.f) + EPS) * omli;
;         bf16_t* ap = aout + (size_t)q * 1024 + head * 128 + 4 * hh;
; #pragma unroll
;         for (int e = 0; e < 4; ++e)
; #pragma unroll
;             for (int g4 = 0; g4 < 4; ++g4) { const int e0 = 32 * e + 8 * g4; const f32x4 sg = *(const f32x4*)(subg + e0 + 4 * hh);
	global_load_dwordx4 v[244:247], v112, s[2:3] offset:448
	global_load_dwordx4 v[248:251], v112, s[2:3] offset:480
	v_pk_add_f32 v[48:49], v[48:49], v[50:51] op_sel_hi:[1,0]
	v_pk_mul_f32 v[50:51], v[200:201], v[130:131]
	s_nop 0
	v_pk_fma_f32 v[54:55], v[34:35], v[70:71], v[50:51] op_sel_hi:[1,0,1] neg_lo:[0,0,1] neg_hi:[0,0,1]
	v_pk_mul_f32 v[34:35], v[200:201], v[128:129]
	s_nop 0
	v_pk_fma_f32 v[60:61], v[32:33], v[70:71], v[34:35] op_sel_hi:[1,0,1] neg_lo:[0,0,1] neg_hi:[0,0,1]
	s_nop 0
	v_pk_fma_f32 v[32:33], v[60:61], v[60:61], v[48:49]
	v_mul_f32_e32 v34, v61, v61
	v_pk_add_f32 v[32:33], v[32:33], v[34:35] op_sel_hi:[1,0]
	v_mul_f32_e32 v34, v55, v55
	v_pk_fma_f32 v[32:33], v[54:55], v[54:55], v[32:33]
	s_nop 0
	v_pk_add_f32 v[32:33], v[32:33], v[34:35] op_sel_hi:[1,0]
	v_pk_mul_f32 v[34:35], v[200:201], v[134:135]
	s_nop 0
	v_pk_fma_f32 v[50:51], v[38:39], v[70:71], v[34:35] op_sel_hi:[1,0,1] neg_lo:[0,0,1] neg_hi:[0,0,1]
	v_pk_mul_f32 v[34:35], v[200:201], v[132:133]
	s_nop 0
	v_pk_fma_f32 v[56:57], v[36:37], v[70:71], v[34:35] op_sel_hi:[1,0,1] neg_lo:[0,0,1] neg_hi:[0,0,1]
	s_nop 0
	v_pk_fma_f32 v[32:33], v[56:57], v[56:57], v[32:33]
	v_mul_f32_e32 v34, v57, v57
	v_pk_add_f32 v[32:33], v[32:33], v[34:35] op_sel_hi:[1,0]
	v_mul_f32_e32 v34, v51, v51
	v_pk_fma_f32 v[32:33], v[50:51], v[50:51], v[32:33]
	s_nop 0
	v_pk_add_f32 v[32:33], v[32:33], v[34:35] op_sel_hi:[1,0]
	v_pk_mul_f32 v[34:35], v[200:201], v[136:137]
	s_nop 0
	v_pk_fma_f32 v[48:49], v[42:43], v[70:71], v[34:35] op_sel_hi:[1,0,1] neg_lo:[0,0,1] neg_hi:[0,0,1]
	v_pk_mul_f32 v[34:35], v[200:201], v[120:121]
	s_nop 0
	v_pk_fma_f32 v[52:53], v[40:41], v[70:71], v[34:35] op_sel_hi:[1,0,1] neg_lo:[0,0,1] neg_hi:[0,0,1]
	s_nop 0
	v_pk_fma_f32 v[32:33], v[52:53], v[52:53], v[32:33]
	v_mul_f32_e32 v34, v53, v53
	v_pk_add_f32 v[32:33], v[32:33], v[34:35] op_sel_hi:[1,0]
	v_mul_f32_e32 v34, v49, v49
	v_pk_fma_f32 v[32:33], v[48:49], v[48:49], v[32:33]
	s_nop 0
	v_pk_add_f32 v[32:33], v[32:33], v[34:35] op_sel_hi:[1,0]
	v_pk_mul_f32 v[34:35], v[200:201], v[118:119]
	s_nop 0
	v_pk_fma_f32 v[40:41], v[46:47], v[70:71], v[34:35] op_sel_hi:[1,0,1] neg_lo:[0,0,1] neg_hi:[0,0,1]
	v_pk_mul_f32 v[34:35], v[200:201], v[116:117]
	s_nop 0
	v_pk_fma_f32 v[44:45], v[44:45], v[70:71], v[34:35] op_sel_hi:[1,0,1] neg_lo:[0,0,1] neg_hi:[0,0,1]
	s_nop 0
	v_pk_fma_f32 v[32:33], v[44:45], v[44:45], v[32:33]
	v_mul_f32_e32 v34, v45, v45
	v_pk_add_f32 v[32:33], v[32:33], v[34:35] op_sel_hi:[1,0]
	v_mul_f32_e32 v34, v41, v41
	v_pk_fma_f32 v[32:33], v[40:41], v[40:41], v[32:33]
	s_nop 0
	v_pk_add_f32 v[32:33], v[32:33], v[34:35] op_sel_hi:[1,0]
	v_pk_mul_f32 v[34:35], v[200:201], v[114:115]
	s_nop 0
	v_pk_fma_f32 v[36:37], v[18:19], v[70:71], v[34:35] op_sel_hi:[1,0,1] neg_lo:[0,0,1] neg_hi:[0,0,1]
	v_pk_mul_f32 v[18:19], v[200:201], v[110:111]
	s_nop 0
	v_pk_fma_f32 v[42:43], v[16:17], v[70:71], v[18:19] op_sel_hi:[1,0,1] neg_lo:[0,0,1] neg_hi:[0,0,1]
	s_nop 0
	v_pk_fma_f32 v[16:17], v[42:43], v[42:43], v[32:33]
	v_mul_f32_e32 v18, v43, v43
	v_pk_add_f32 v[16:17], v[16:17], v[18:19] op_sel_hi:[1,0]
	v_mul_f32_e32 v18, v37, v37
	v_pk_fma_f32 v[16:17], v[36:37], v[36:37], v[16:17]
	s_nop 0
	v_pk_add_f32 v[16:17], v[16:17], v[18:19] op_sel_hi:[1,0]
	v_pk_mul_f32 v[18:19], v[200:201], v[108:109]
	s_nop 0
	v_pk_fma_f32 v[32:33], v[22:23], v[70:71], v[18:19] op_sel_hi:[1,0,1] neg_lo:[0,0,1] neg_hi:[0,0,1]
	v_pk_mul_f32 v[18:19], v[200:201], v[106:107]
	s_nop 0
	v_pk_fma_f32 v[38:39], v[20:21], v[70:71], v[18:19] op_sel_hi:[1,0,1] neg_lo:[0,0,1] neg_hi:[0,0,1]
	s_nop 0
	v_pk_fma_f32 v[16:17], v[38:39], v[38:39], v[16:17]
	v_mul_f32_e32 v18, v39, v39
	v_pk_add_f32 v[16:17], v[16:17], v[18:19] op_sel_hi:[1,0]
	v_mul_f32_e32 v18, v33, v33
	v_pk_fma_f32 v[16:17], v[32:33], v[32:33], v[16:17]
	s_nop 0
	v_pk_add_f32 v[16:17], v[16:17], v[18:19] op_sel_hi:[1,0]
	v_pk_mul_f32 v[18:19], v[200:201], v[104:105]
	s_nop 0
	v_pk_fma_f32 v[26:27], v[26:27], v[70:71], v[18:19] op_sel_hi:[1,0,1] neg_lo:[0,0,1] neg_hi:[0,0,1]
	v_pk_mul_f32 v[18:19], v[200:201], v[98:99]
	s_nop 0
	v_pk_fma_f32 v[34:35], v[24:25], v[70:71], v[18:19] op_sel_hi:[1,0,1] neg_lo:[0,0,1] neg_hi:[0,0,1]
	s_nop 0
	v_pk_fma_f32 v[16:17], v[34:35], v[34:35], v[16:17]
	v_mul_f32_e32 v18, v35, v35
	v_pk_add_f32 v[16:17], v[16:17], v[18:19] op_sel_hi:[1,0]
	v_mul_f32_e32 v18, v27, v27
	v_pk_fma_f32 v[16:17], v[26:27], v[26:27], v[16:17]
	s_nop 0
	v_pk_add_f32 v[16:17], v[16:17], v[18:19] op_sel_hi:[1,0]
	v_pk_mul_f32 v[18:19], v[200:201], v[96:97]
	s_nop 0
	v_pk_fma_f32 v[20:21], v[30:31], v[70:71], v[18:19] op_sel_hi:[1,0,1] neg_lo:[0,0,1] neg_hi:[0,0,1]
	v_pk_mul_f32 v[18:19], v[200:201], v[88:89]
	s_nop 0
	v_pk_fma_f32 v[24:25], v[28:29], v[70:71], v[18:19] op_sel_hi:[1,0,1] neg_lo:[0,0,1] neg_hi:[0,0,1]
	s_nop 0
	v_pk_fma_f32 v[16:17], v[24:25], v[24:25], v[16:17]
	v_mul_f32_e32 v18, v25, v25
	v_pk_add_f32 v[16:17], v[16:17], v[18:19] op_sel_hi:[1,0]
	v_mul_f32_e32 v18, v21, v21
	v_pk_fma_f32 v[16:17], v[20:21], v[20:21], v[16:17]
	s_nop 0
	v_pk_add_f32 v[18:19], v[16:17], v[18:19] op_sel_hi:[1,0]
	v_pk_mul_f32 v[16:17], v[200:201], v[86:87]
	s_nop 0
	v_pk_fma_f32 v[16:17], v[2:3], v[70:71], v[16:17] op_sel_hi:[1,0,1] neg_lo:[0,0,1] neg_hi:[0,0,1]
	v_pk_mul_f32 v[2:3], v[200:201], v[82:83]
	s_nop 0
	v_pk_fma_f32 v[22:23], v[0:1], v[70:71], v[2:3] op_sel_hi:[1,0,1] neg_lo:[0,0,1] neg_hi:[0,0,1]
	s_nop 0
	v_pk_fma_f32 v[0:1], v[22:23], v[22:23], v[18:19]
	v_mul_f32_e32 v2, v23, v23
	v_pk_add_f32 v[0:1], v[0:1], v[2:3] op_sel_hi:[1,0]
	v_mul_f32_e32 v2, v17, v17
	v_pk_fma_f32 v[0:1], v[16:17], v[16:17], v[0:1]
	s_nop 0
	v_pk_add_f32 v[0:1], v[0:1], v[2:3] op_sel_hi:[1,0]
; __device__ __forceinline__ float half_swap_sum(float v) { auto rr = __builtin_amdgcn_permlane32_swap(__float_as_uint(v), __float_as_uint(v), false, false); return __uint_as_float(rr[0]) + __uint_as_float(rr[1]); }
; __device__ __forceinline__ void attn_item(LAS unsigned char* lds, const bf16_t* Q, const bf16_t* Kb, const bf16_t* VT, bf16_t* aout, const float* subg, float lam, float omli, float kbound, int head, int qb) {
;     ...
;             for (int i = 0; i < 16; ++i) { const float o = O[e][i] * inv - lam * X[(qt * 128 + 32 * e + (i & 3) + 8 * (i >> 2) + 4 * hh) * 32 + r]; O[e][i] = o; ss += o * o; }
;         ss = half_swap_sum(ss);
;         const float rn = __builtin_amdgcn_rsqf(ss * (1.f / 128.f) + EPS) * omli;
	v_pk_mul_f32 v[2:3], v[200:201], v[80:81]
	s_nop 0
	v_pk_fma_f32 v[6:7], v[6:7], v[70:71], v[2:3] op_sel_hi:[1,0,1] neg_lo:[0,0,1] neg_hi:[0,0,1]
	v_pk_mul_f32 v[2:3], v[200:201], v[78:79]
	s_nop 0
	v_pk_fma_f32 v[18:19], v[4:5], v[70:71], v[2:3] op_sel_hi:[1,0,1] neg_lo:[0,0,1] neg_hi:[0,0,1]
	v_pk_mul_f32 v[4:5], v[200:201], v[72:73]
	v_pk_fma_f32 v[0:1], v[18:19], v[18:19], v[0:1]
	v_mul_f32_e32 v2, v19, v19
	v_pk_add_f32 v[0:1], v[0:1], v[2:3] op_sel_hi:[1,0]
	v_mul_f32_e32 v2, v7, v7
	v_pk_fma_f32 v[0:1], v[6:7], v[6:7], v[0:1]
	v_pk_fma_f32 v[4:5], v[8:9], v[70:71], v[4:5] op_sel_hi:[1,0,1] neg_lo:[0,0,1] neg_hi:[0,0,1]
	v_pk_add_f32 v[2:3], v[0:1], v[2:3] op_sel_hi:[1,0]
	v_pk_mul_f32 v[0:1], v[200:201], v[76:77]
	v_pk_fma_f32 v[2:3], v[4:5], v[4:5], v[2:3]
	v_mul_f32_e32 v8, v5, v5
	v_pk_fma_f32 v[0:1], v[10:11], v[70:71], v[0:1] op_sel_hi:[1,0,1] neg_lo:[0,0,1] neg_hi:[0,0,1]
	v_pk_add_f32 v[2:3], v[2:3], v[8:9] op_sel_hi:[1,0]
	v_mul_f32_e32 v8, v1, v1
	v_pk_fma_f32 v[2:3], v[0:1], v[0:1], v[2:3]
	s_nop 0
	v_pk_add_f32 v[8:9], v[2:3], v[8:9] op_sel_hi:[1,0]
	v_pk_mul_f32 v[2:3], v[200:201], v[74:75]
	s_nop 0
	v_pk_fma_f32 v[2:3], v[12:13], v[70:71], v[2:3] op_sel_hi:[1,0,1] neg_lo:[0,0,1] neg_hi:[0,0,1]
	s_nop 0
	v_pk_fma_f32 v[8:9], v[2:3], v[2:3], v[8:9]
	v_mul_f32_e32 v10, v3, v3
	v_pk_add_f32 v[8:9], v[8:9], v[10:11] op_sel_hi:[1,0]
	v_mul_f32_e32 v10, v69, v69
	v_pk_fma_f32 v[8:9], v[68:69], v[68:69], v[8:9]
	s_nop 0
	v_pk_add_f32 v[8:9], v[8:9], v[10:11] op_sel_hi:[1,0]
	s_nop 0
	v_mov_b32_e32 v9, v8
	s_nop 1
	v_permlane32_swap_b32_e32 v8, v9
	v_add_f32_e32 v8, v8, v9
	v_fmamk_f32 v8, v8, 0x3c000000, v217
	v_rsq_f32_e32 v8, v8
	s_nop 0
	v_mul_f32_e32 v8, v224, v8
	v_pk_mul_f32 v[10:11], v[90:91], v[8:9] op_sel_hi:[1,0]
	v_pk_mul_f32 v[12:13], v[84:85], v[8:9] op_sel_hi:[1,0]
	s_waitcnt vmcnt(0)
; __device__ __forceinline__ unsigned pk2(float lo, float hi) { f32x2 v = {lo, hi}; bf16x2_t b = __builtin_convertvector(v, bf16x2_t); return __builtin_bit_cast(unsigned, b); }
; __device__ __forceinline__ void attn_item(LAS unsigned char* lds, const bf16_t* Q, const bf16_t* Kb, const bf16_t* VT, bf16_t* aout, const float* subg, float lam, float omli, float kbound, int head, int qb) {
;     ...
;         bf16_t* ap = aout + (size_t)q * 1024 + head * 128 + 4 * hh;
; #pragma unroll
;         for (int e = 0; e < 4; ++e)
; #pragma unroll
;             for (int g4 = 0; g4 < 4; ++g4) { const int e0 = 32 * e + 8 * g4; const f32x4 sg = *(const f32x4*)(subg + e0 + 4 * hh);
;                 u32x2 w; w.x = pk2(O[e][4 * g4 + 0] * rn * sg[0], O[e][4 * g4 + 1] * rn * sg[1]); w.y = pk2(O[e][4 * g4 + 2] * rn * sg[2], O[e][4 * g4 + 3] * rn * sg[3]);
;                 *(u32x2*)(ap + e0) = w; }
	v_pk_mul_f32 v[10:11], v[64:65], v[10:11]
	v_pk_mul_f32 v[12:13], v[66:67], v[12:13]
	v_cvt_pk_bf16_f32 v10, v10, v11
	v_cvt_pk_bf16_f32 v11, v12, v13
	global_store_dwordx2 v[14:15], v[10:11], off
	s_nop 1
	v_pk_mul_f32 v[28:29], v[100:101], v[8:9] op_sel_hi:[1,0]
	v_pk_mul_f32 v[26:27], v[26:27], v[8:9] op_sel_hi:[1,0]
	v_pk_mul_f32 v[24:25], v[24:25], v[8:9] op_sel_hi:[1,0]
	v_pk_mul_f32 v[20:21], v[20:21], v[8:9] op_sel_hi:[1,0]
	v_pk_mul_f32 v[16:17], v[16:17], v[8:9] op_sel_hi:[1,0]
	v_pk_mul_f32 v[6:7], v[6:7], v[8:9] op_sel_hi:[1,0]
	v_pk_mul_f32 v[4:5], v[4:5], v[8:9] op_sel_hi:[1,0]
	v_pk_mul_f32 v[0:1], v[0:1], v[8:9] op_sel_hi:[1,0]
	v_pk_mul_f32 v[10:11], v[148:149], v[28:29]
	v_pk_mul_f32 v[28:29], v[92:93], v[8:9] op_sel_hi:[1,0]
	v_cvt_pk_bf16_f32 v10, v10, v11
	v_pk_mul_f32 v[12:13], v[150:151], v[28:29]
	v_pk_mul_f32 v[28:29], v[102:103], v[8:9] op_sel_hi:[1,0]
	v_cvt_pk_bf16_f32 v11, v12, v13
	global_store_dwordx2 v[14:15], v[10:11], off offset:16
	s_nop 1
	v_pk_mul_f32 v[10:11], v[152:153], v[28:29]
	v_pk_mul_f32 v[28:29], v[94:95], v[8:9] op_sel_hi:[1,0]
	v_cvt_pk_bf16_f32 v10, v10, v11
	v_pk_mul_f32 v[12:13], v[154:155], v[28:29]
	v_pk_mul_f32 v[28:29], v[62:63], v[8:9] op_sel_hi:[1,0]
	v_cvt_pk_bf16_f32 v11, v12, v13
	global_store_dwordx2 v[14:15], v[10:11], off offset:32
	s_nop 1
	v_pk_mul_f32 v[10:11], v[156:157], v[28:29]
	v_pk_mul_f32 v[28:29], v[58:59], v[8:9] op_sel_hi:[1,0]
	v_cvt_pk_bf16_f32 v10, v10, v11
	v_pk_mul_f32 v[12:13], v[158:159], v[28:29]
	v_pk_mul_f32 v[28:29], v[60:61], v[8:9] op_sel_hi:[1,0]
	v_cvt_pk_bf16_f32 v11, v12, v13
	global_store_dwordx2 v[14:15], v[10:11], off offset:48
	s_nop 1
	v_pk_mul_f32 v[10:11], v[28:29], v[160:161]
	v_pk_mul_f32 v[28:29], v[54:55], v[8:9] op_sel_hi:[1,0]
	v_cvt_pk_bf16_f32 v10, v10, v11
	v_pk_mul_f32 v[12:13], v[28:29], v[162:163]
	v_pk_mul_f32 v[28:29], v[56:57], v[8:9] op_sel_hi:[1,0]
	v_cvt_pk_bf16_f32 v11, v12, v13
	global_store_dwordx2 v[14:15], v[10:11], off offset:64
	s_nop 1
	v_pk_mul_f32 v[10:11], v[28:29], v[164:165]
	v_pk_mul_f32 v[28:29], v[50:51], v[8:9] op_sel_hi:[1,0]
	v_cvt_pk_bf16_f32 v10, v10, v11
	v_pk_mul_f32 v[12:13], v[28:29], v[166:167]
	v_pk_mul_f32 v[28:29], v[52:53], v[8:9] op_sel_hi:[1,0]
	v_cvt_pk_bf16_f32 v11, v12, v13
	global_store_dwordx2 v[14:15], v[10:11], off offset:80
	s_nop 1
	v_pk_mul_f32 v[10:11], v[28:29], v[168:169]
	v_pk_mul_f32 v[28:29], v[48:49], v[8:9] op_sel_hi:[1,0]
	v_cvt_pk_bf16_f32 v10, v10, v11
	v_pk_mul_f32 v[12:13], v[28:29], v[170:171]
	v_pk_mul_f32 v[28:29], v[44:45], v[8:9] op_sel_hi:[1,0]
	v_cvt_pk_bf16_f32 v11, v12, v13
	global_store_dwordx2 v[14:15], v[10:11], off offset:96
	s_nop 1
	v_pk_mul_f32 v[10:11], v[28:29], v[176:177]
	v_pk_mul_f32 v[28:29], v[40:41], v[8:9] op_sel_hi:[1,0]
	v_cvt_pk_bf16_f32 v10, v10, v11
	v_pk_mul_f32 v[12:13], v[28:29], v[178:179]
	v_pk_mul_f32 v[28:29], v[42:43], v[8:9] op_sel_hi:[1,0]
	v_cvt_pk_bf16_f32 v11, v12, v13
	global_store_dwordx2 v[14:15], v[10:11], off offset:112
	s_nop 1
	v_pk_mul_f32 v[10:11], v[28:29], v[184:185]
	v_pk_mul_f32 v[28:29], v[36:37], v[8:9] op_sel_hi:[1,0]
	v_cvt_pk_bf16_f32 v10, v10, v11
	v_pk_mul_f32 v[12:13], v[28:29], v[186:187]
	v_pk_mul_f32 v[28:29], v[38:39], v[8:9] op_sel_hi:[1,0]
	v_cvt_pk_bf16_f32 v11, v12, v13
	global_store_dwordx2 v[14:15], v[10:11], off offset:128
	s_nop 1
	v_pk_mul_f32 v[10:11], v[28:29], v[204:205]
	v_pk_mul_f32 v[28:29], v[32:33], v[8:9] op_sel_hi:[1,0]
	v_cvt_pk_bf16_f32 v10, v10, v11
	v_pk_mul_f32 v[12:13], v[28:29], v[206:207]
	v_pk_mul_f32 v[28:29], v[34:35], v[8:9] op_sel_hi:[1,0]
	v_cvt_pk_bf16_f32 v11, v12, v13
	global_store_dwordx2 v[14:15], v[10:11], off offset:144
	s_nop 1
	v_pk_mul_f32 v[10:11], v[28:29], v[208:209]
	v_pk_mul_f32 v[12:13], v[26:27], v[210:211]
	v_cvt_pk_bf16_f32 v10, v10, v11
	v_cvt_pk_bf16_f32 v11, v12, v13
	global_store_dwordx2 v[14:15], v[10:11], off offset:160
	s_nop 1
	v_pk_mul_f32 v[10:11], v[24:25], v[232:233]
	v_pk_mul_f32 v[12:13], v[20:21], v[234:235]
	v_cvt_pk_bf16_f32 v10, v10, v11
	v_cvt_pk_bf16_f32 v11, v12, v13
	global_store_dwordx2 v[14:15], v[10:11], off offset:176
	s_nop 1
	v_pk_mul_f32 v[20:21], v[22:23], v[8:9] op_sel_hi:[1,0]
	v_pk_mul_f32 v[12:13], v[16:17], v[238:239]
	v_pk_mul_f32 v[10:11], v[20:21], v[236:237]
	v_pk_mul_f32 v[16:17], v[18:19], v[8:9] op_sel_hi:[1,0]
	v_cvt_pk_bf16_f32 v10, v10, v11
	v_cvt_pk_bf16_f32 v11, v12, v13
	global_store_dwordx2 v[14:15], v[10:11], off offset:192
	s_nop 1
	v_pk_mul_f32 v[10:11], v[16:17], v[240:241]
	v_pk_mul_f32 v[6:7], v[6:7], v[242:243]
	v_cvt_pk_bf16_f32 v10, v10, v11
	v_cvt_pk_bf16_f32 v11, v6, v7
	global_store_dwordx2 v[14:15], v[10:11], off offset:208
	s_nop 1
	v_pk_mul_f32 v[4:5], v[4:5], v[244:245]
	v_pk_mul_f32 v[0:1], v[0:1], v[246:247]
	v_cvt_pk_bf16_f32 v4, v4, v5
	v_cvt_pk_bf16_f32 v5, v0, v1
	global_store_dwordx2 v[14:15], v[4:5], off offset:224
	s_nop 1
	v_pk_mul_f32 v[0:1], v[2:3], v[8:9] op_sel_hi:[1,0]
	v_pk_mul_f32 v[2:3], v[68:69], v[8:9] op_sel_hi:[1,0]
	v_pk_mul_f32 v[0:1], v[0:1], v[248:249]
	v_pk_mul_f32 v[2:3], v[2:3], v[250:251]
	v_cvt_pk_bf16_f32 v0, v0, v1
	v_cvt_pk_bf16_f32 v1, v2, v3
	global_store_dwordx2 v[14:15], v[0:1], off offset:240
	s_nop 1
	s_branch .LBB0_291
